# attention softmax fronts (FoX and MLA tile bodies) rewritten with packed f32 ops (v_pk_fma_f32 / v_pk_add_f32), bpermute indices simplified; per-element v_exp_f32 unchanged
# baseline (speedup 1.0000x reference)
; DEVI unsigned pk_bf16(float lo, float hi) { unsigned r; asm("v_cvt_pk_bf16_f32 %0, %1, %2" : "=v"(r) : "v"(lo), "v"(hi)); return r; }
; DEVI bf16x8 mk8(uint2 a, uint2 b) { union { uint4 u; bf16x8 v; } c; c.u = make_uint4(a.x, a.y, b.x, b.y); return c.v; }
; template <int DK, bool BIAS> ...
;     ...
;       for (int qi = 0; qi < 2; ++qi) {
;         float mx = -3e38f;
;         if (BIAS) {
; #pragma unroll
;           for (int kt = 0; kt < 4; ++kt) { const f32x4 nf = *(const f32x4*)(fkm + buf * 64 + 16 * kt + 4 * fq);
; #pragma unroll
;             for (int r = 0; r < 4; ++r) { const float t = fmaf(S[kt][qi][r], sc2, nf[r]); S[kt][qi][r] = t; mx = fmaxf(mx, t); } }
;         } else {
; #pragma unroll
;           for (int kt = 0; kt < 4; ++kt)
; #pragma unroll
;             for (int r = 0; r < 4; ++r) mx = fmaxf(mx, S[kt][qi][r]);
;           mx *= sc2;
;         }
;         mx = fmaxf(mx, __shfl_xor(mx, 16)); mx = fmaxf(mx, __shfl_xor(mx, 32));
;         const float mold = mrun[qi], mnew = fmaxf(mold, mx);
;         mrun[qi] = mnew;
;         float ps = 0.f;
; #pragma unroll
;         for (int kt = 0; kt < 4; ++kt)
; #pragma unroll
;           for (int r = 0; r < 4; ++r) { const float pv = BIAS ? __builtin_amdgcn_exp2f(S[kt][qi][r] - mnew) : __builtin_amdgcn_exp2f(fmaf(S[kt][qi][r], sc2, -mnew)); S[kt][qi][r] = pv; ps += pv; }
;         {
;           const float alpha = __builtin_amdgcn_exp2f(mold - mnew);
;           lrun[qi] *= alpha;
; #pragma unroll
;           for (int et = 0; et < 4; ++et) O[et][qi] *= alpha;
;         }
;         lrun[qi] += ps;
; #pragma unroll
;         for (int k2 = 0; k2 < 2; ++k2) { uint2 lo, hi; lo.x = pk_bf16(S[2 * k2][qi][0], S[2 * k2][qi][1]); lo.y = pk_bf16(S[2 * k2][qi][2], S[2 * k2][qi][3]);
;           hi.x = pk_bf16(S[2 * k2 + 1][qi][0], S[2 * k2 + 1][qi][1]); hi.y = pk_bf16(S[2 * k2 + 1][qi][2], S[2 * k2 + 1][qi][3]); pf[qi][k2] = mk8(lo, hi); }
;       }
.LBB0_1776:
	s_or_b64 exec, exec, s[18:19]
	ds_read_b128 v[174:177], v168 offset:36864
	ds_read_b128 v[194:197], v168 offset:36928
	ds_read_b128 v[242:245], v168 offset:36992
	ds_read_b128 v[246:249], v168 offset:37056
	s_mov_b32 s100, 0x3e38aa3b
	s_mov_b32 s101, 0x3e38aa3b
	v_lshlrev_b32_e32 v250, 2, v186
	v_lshlrev_b32_e32 v251, 2, v185
	s_waitcnt lgkmcnt(3)
	v_pk_fma_f32 v[210:211], v[80:81], s[100:101], v[174:175]
	v_pk_fma_f32 v[212:213], v[82:83], s[100:101], v[176:177]
	v_pk_fma_f32 v[226:227], v[64:65], s[100:101], v[174:175]
	v_pk_fma_f32 v[228:229], v[66:67], s[100:101], v[176:177]
	s_waitcnt lgkmcnt(2)
	v_pk_fma_f32 v[214:215], v[86:87], s[100:101], v[194:195]
	v_pk_fma_f32 v[216:217], v[88:89], s[100:101], v[196:197]
	v_pk_fma_f32 v[230:231], v[68:69], s[100:101], v[194:195]
	v_pk_fma_f32 v[232:233], v[70:71], s[100:101], v[196:197]
	s_waitcnt lgkmcnt(1)
	v_pk_fma_f32 v[218:219], v[90:91], s[100:101], v[242:243]
	v_pk_fma_f32 v[220:221], v[92:93], s[100:101], v[244:245]
	v_pk_fma_f32 v[234:235], v[72:73], s[100:101], v[242:243]
	v_pk_fma_f32 v[236:237], v[74:75], s[100:101], v[244:245]
	s_waitcnt lgkmcnt(0)
	v_pk_fma_f32 v[222:223], v[94:95], s[100:101], v[246:247]
	v_pk_fma_f32 v[224:225], v[96:97], s[100:101], v[248:249]
	v_pk_fma_f32 v[238:239], v[76:77], s[100:101], v[246:247]
	v_pk_fma_f32 v[240:241], v[78:79], s[100:101], v[248:249]
	v_max3_f32 v84, v210, s31, v211
	v_max3_f32 v85, v226, s31, v227
	v_max3_f32 v84, v84, v212, v213
	v_max3_f32 v85, v85, v228, v229
	v_max3_f32 v84, v84, v214, v215
	v_max3_f32 v85, v85, v230, v231
	v_max3_f32 v84, v84, v216, v217
	v_max3_f32 v85, v85, v232, v233
	v_max3_f32 v84, v84, v218, v219
	v_max3_f32 v85, v85, v234, v235
	v_max3_f32 v84, v84, v220, v221
	v_max3_f32 v85, v85, v236, v237
	v_max3_f32 v84, v84, v222, v223
	v_max3_f32 v85, v85, v238, v239
	v_max3_f32 v84, v84, v224, v225
	v_max3_f32 v85, v85, v240, v241
	ds_bpermute_b32 v86, v250, v84
	ds_bpermute_b32 v87, v250, v85
	s_waitcnt lgkmcnt(0)
	v_max_f32_e32 v84, v84, v86
	v_max_f32_e32 v85, v85, v87
	ds_bpermute_b32 v86, v251, v84
	ds_bpermute_b32 v87, v251, v85
	s_waitcnt lgkmcnt(0)
	v_max3_f32 v131, v114, v84, v86
	v_max3_f32 v173, v112, v85, v87
	v_sub_f32_e32 v84, v114, v131
	v_sub_f32_e32 v85, v112, v173
	v_exp_f32_e32 v126, v84
	v_exp_f32_e32 v82, v85
	v_sub_f32_e32 v86, 0, v131
	v_sub_f32_e32 v80, 0, v173
	v_pk_add_f32 v[210:211], v[210:211], v[86:87] op_sel_hi:[1,0]
	v_pk_add_f32 v[212:213], v[212:213], v[86:87] op_sel_hi:[1,0]
	v_pk_add_f32 v[226:227], v[226:227], v[80:81] op_sel_hi:[1,0]
	v_pk_add_f32 v[228:229], v[228:229], v[80:81] op_sel_hi:[1,0]
	v_pk_add_f32 v[214:215], v[214:215], v[86:87] op_sel_hi:[1,0]
	v_pk_add_f32 v[216:217], v[216:217], v[86:87] op_sel_hi:[1,0]
	v_pk_add_f32 v[230:231], v[230:231], v[80:81] op_sel_hi:[1,0]
	v_pk_add_f32 v[232:233], v[232:233], v[80:81] op_sel_hi:[1,0]
	v_pk_add_f32 v[218:219], v[218:219], v[86:87] op_sel_hi:[1,0]
	v_pk_add_f32 v[220:221], v[220:221], v[86:87] op_sel_hi:[1,0]
	v_pk_add_f32 v[234:235], v[234:235], v[80:81] op_sel_hi:[1,0]
	v_pk_add_f32 v[236:237], v[236:237], v[80:81] op_sel_hi:[1,0]
	v_pk_add_f32 v[222:223], v[222:223], v[86:87] op_sel_hi:[1,0]
	v_pk_add_f32 v[224:225], v[224:225], v[86:87] op_sel_hi:[1,0]
	v_pk_add_f32 v[238:239], v[238:239], v[80:81] op_sel_hi:[1,0]
	v_pk_add_f32 v[240:241], v[240:241], v[80:81] op_sel_hi:[1,0]
	v_exp_f32_e32 v155, v210
	v_exp_f32_e32 v154, v226
	v_exp_f32_e32 v157, v211
	v_exp_f32_e32 v156, v227
	v_exp_f32_e32 v151, v212
	v_exp_f32_e32 v150, v228
	v_exp_f32_e32 v153, v213
	v_exp_f32_e32 v152, v229
	v_exp_f32_e32 v117, v214
	v_exp_f32_e32 v116, v230
	v_exp_f32_e32 v119, v215
	v_exp_f32_e32 v118, v231
	v_exp_f32_e32 v123, v216
	v_exp_f32_e32 v122, v232
	v_exp_f32_e32 v121, v217
	v_exp_f32_e32 v120, v233
	v_exp_f32_e32 v125, v218
	v_exp_f32_e32 v124, v234
	v_exp_f32_e32 v89, v219
	v_exp_f32_e32 v88, v235
	v_exp_f32_e32 v95, v220
	v_exp_f32_e32 v94, v236
	v_exp_f32_e32 v115, v221
	v_exp_f32_e32 v114, v237
	v_exp_f32_e32 v93, v222
	v_exp_f32_e32 v92, v238
	v_exp_f32_e32 v113, v223
	v_exp_f32_e32 v112, v239
	v_exp_f32_e32 v91, v224
	v_exp_f32_e32 v90, v240
	v_exp_f32_e32 v97, v225
	v_exp_f32_e32 v96, v241
	v_pk_mul_f32 v[202:203], v[52:53], v[126:127] op_sel_hi:[1,0]
	v_pk_mul_f32 v[52:53], v[56:57], v[126:127] op_sel_hi:[1,0]
	v_pk_mul_f32 v[198:199], v[48:49], v[126:127] op_sel_hi:[1,0]
	v_pk_mul_f32 v[48:49], v[60:61], v[126:127] op_sel_hi:[1,0]
	v_add_u32_e32 v174, 0x4800, v170
	v_add_u32_e32 v175, 0x5000, v170
	v_pk_mul_f32 v[200:201], v[50:51], v[126:127] op_sel_hi:[1,0]
	v_add_u32_e32 v176, 0x5800, v170
	v_pk_mul_f32 v[204:205], v[54:55], v[126:127] op_sel_hi:[1,0]
	v_pk_add_f32 v[64:65], v[154:155], 0 op_sel_hi:[1,0]
	v_pk_add_f32 v[80:81], v[156:157], v[64:65]
	ds_read2_b64 v[64:67], v174 offset1:4
	ds_read2_b64 v[72:75], v175 offset0:32 offset1:36
	v_pk_mul_f32 v[46:47], v[46:47], v[82:83] op_sel_hi:[1,0]
	v_pk_mul_f32 v[44:45], v[44:45], v[82:83] op_sel_hi:[1,0]
	v_pk_mul_f32 v[54:55], v[58:59], v[126:127] op_sel_hi:[1,0]
	v_cvt_pk_bf16_f32 v56, v155, v157
	v_cvt_pk_bf16_f32 v57, v151, v153
	v_cvt_pk_bf16_f32 v58, v117, v119
	v_cvt_pk_bf16_f32 v59, v123, v121
	v_cvt_pk_bf16_f32 v68, v154, v156
	s_waitcnt lgkmcnt(1)
; DEVI unsigned pk_bf16(float lo, float hi) { unsigned r; asm("v_cvt_pk_bf16_f32 %0, %1, %2" : "=v"(r) : "v"(lo), "v"(hi)); return r; }
; DEVI bf16x8 mk8(uint2 a, uint2 b) { union { uint4 u; bf16x8 v; } c; c.u = make_uint4(a.x, a.y, b.x, b.y); return c.v; }
; #define MFMA(a, b, c) __builtin_amdgcn_mfma_f32_16x16x32_bf16((a), (b), (c), 0, 0, 0)
; template <int DK, bool BIAS> ...
;     ...
;         {
;           const float alpha = __builtin_amdgcn_exp2f(mold - mnew);
;           lrun[qi] *= alpha;
; #pragma unroll
;           for (int et = 0; et < 4; ++et) O[et][qi] *= alpha;
;         }
;         lrun[qi] += ps;
; #pragma unroll
;         for (int k2 = 0; k2 < 2; ++k2) { uint2 lo, hi; lo.x = pk_bf16(S[2 * k2][qi][0], S[2 * k2][qi][1]); lo.y = pk_bf16(S[2 * k2][qi][2], S[2 * k2][qi][3]);
;           hi.x = pk_bf16(S[2 * k2 + 1][qi][0], S[2 * k2 + 1][qi][1]); hi.y = pk_bf16(S[2 * k2 + 1][qi][2], S[2 * k2 + 1][qi][3]); pf[qi][k2] = mk8(lo, hi); }
;       }
; #pragma unroll
;       for (int k2 = 0; k2 < 2; ++k2)
; #pragma unroll
;         for (int et = 0; et < 4; ++et) {
;           const uint2 v0 = *(const uint2*)(Vtm + (buf * 64 + 16 * et + fr) * 72 + 32 * k2 + 4 * fq), v1 = *(const uint2*)(Vtm + (buf * 64 + 16 * et + fr) * 72 + 32 * k2 + 16 + 4 * fq);
;           const bf16x8 va = mk8(v0, v1);
; #pragma unroll
;           for (int qi = 0; qi < 2; ++qi) O[et][qi] = MFMA(va, pf[qi][k2], O[et][qi]);
;         }
	v_mfma_f32_16x16x32_bf16 v[76:79], v[64:67], v[56:59], v[198:201]
	v_cvt_pk_bf16_f32 v69, v150, v152
	v_cvt_pk_bf16_f32 v70, v116, v118
	v_cvt_pk_bf16_f32 v71, v122, v120
	v_mul_f32_e64 v42, v42, v82
	v_mul_f32_e64 v43, v43, v82
	v_mfma_f32_16x16x32_bf16 v[44:47], v[64:67], v[68:71], v[44:47]
	ds_read2_b64 v[64:67], v176 offset0:64 offset1:68
	v_pk_mul_f32 v[40:41], v[40:41], v[82:83] op_sel_hi:[1,0]
	v_add_u32_e32 v177, 0x6000, v170
	s_waitcnt lgkmcnt(1)
	v_mfma_f32_16x16x32_bf16 v[84:87], v[72:75], v[56:59], v[202:205]
	v_pk_mul_f32 v[50:51], v[62:63], v[126:127] op_sel_hi:[1,0]
	v_mfma_f32_16x16x32_bf16 v[40:43], v[72:75], v[68:71], v[40:43]
	ds_read2_b64 v[72:75], v177 offset0:96 offset1:100
	v_pk_mul_f32 v[38:39], v[38:39], v[82:83] op_sel_hi:[1,0]
	v_pk_mul_f32 v[36:37], v[36:37], v[82:83] op_sel_hi:[1,0]
	s_waitcnt lgkmcnt(1)
	v_mfma_f32_16x16x32_bf16 v[154:157], v[64:67], v[56:59], v[52:55]
	v_mul_f32_e64 v34, v34, v82
	v_mul_f32_e64 v35, v35, v82
	v_pk_mul_f32 v[32:33], v[32:33], v[82:83] op_sel_hi:[1,0]
	v_cvt_pk_bf16_f32 v60, v125, v89
	v_mfma_f32_16x16x32_bf16 v[36:39], v[64:67], v[68:71], v[36:39]
	ds_read2_b64 v[52:55], v174 offset0:8 offset1:12
	s_waitcnt lgkmcnt(1)
	v_mfma_f32_16x16x32_bf16 v[64:67], v[72:75], v[56:59], v[48:51]
	ds_read2_b64 v[56:59], v175 offset0:40 offset1:44
	v_cvt_pk_bf16_f32 v61, v95, v115
	v_cvt_pk_bf16_f32 v62, v93, v113
	v_cvt_pk_bf16_f32 v63, v91, v97
	s_nop 0
	v_mfma_f32_16x16x32_bf16 v[32:35], v[72:75], v[68:71], v[32:35]
	v_cvt_pk_bf16_f32 v68, v124, v88
	v_cvt_pk_bf16_f32 v69, v94, v114
	s_waitcnt lgkmcnt(1)
	v_mfma_f32_16x16x32_bf16 v[48:51], v[52:55], v[60:63], v[76:79]
	v_cvt_pk_bf16_f32 v70, v92, v112
	v_cvt_pk_bf16_f32 v71, v90, v96
	ds_read2_b64 v[72:75], v176 offset0:72 offset1:76
	s_nop 0
	v_mfma_f32_16x16x32_bf16 v[44:47], v[52:55], v[68:71], v[44:47]
	v_add_f32_e64 v52, v150, v80
	v_add_f32_e64 v53, v151, v81
	v_mov_b32_e32 v83, v126
	v_pk_add_f32 v[76:77], v[152:153], v[52:53]
	s_waitcnt lgkmcnt(1)
	v_mfma_f32_16x16x32_bf16 v[52:55], v[56:59], v[60:63], v[84:87]
	v_add_f32_e64 v76, v116, v76
	v_add_f32_e64 v77, v117, v77
	v_pk_add_f32 v[76:77], v[118:119], v[76:77]
	v_mfma_f32_16x16x32_bf16 v[40:43], v[56:59], v[68:71], v[40:43]
	v_add_f32_e64 v76, v122, v76
	v_add_f32_e64 v77, v123, v77
	v_pk_add_f32 v[56:57], v[120:121], v[76:77]
	ds_read2_b64 v[76:79], v177 offset0:104 offset1:108
	v_pk_add_f32 v[80:81], v[124:125], v[56:57]
	s_waitcnt lgkmcnt(1)
	v_mfma_f32_16x16x32_bf16 v[56:59], v[72:75], v[60:63], v[154:157]
	v_add_f32_e64 v80, v88, v80
	v_add_f32_e64 v81, v89, v81
	v_pk_add_f32 v[80:81], v[94:95], v[80:81]
	v_mfma_f32_16x16x32_bf16 v[36:39], v[72:75], v[68:71], v[36:39]
	v_add_f32_e64 v80, v114, v80
	v_add_f32_e64 v81, v115, v81
	v_mov_b32_e32 v114, v131
	v_pk_add_f32 v[72:73], v[92:93], v[80:81]
	s_waitcnt lgkmcnt(0)
	v_mfma_f32_16x16x32_bf16 v[60:63], v[76:79], v[60:63], v[64:67]
	v_add_f32_e64 v72, v112, v72
	v_add_f32_e64 v73, v113, v73
	v_mov_b32_e32 v112, v173
	v_mfma_f32_16x16x32_bf16 v[32:35], v[76:79], v[68:71], v[32:35]
	v_add_f32_e64 v64, v90, v72
	v_add_f32_e64 v65, v91, v73
	v_pk_add_f32 v[64:65], v[96:97], v[64:65]
	s_nop 0
	v_pk_fma_f32 v[106:107], v[106:107], v[82:83], v[64:65]

; DEVI unsigned pk_bf16(float lo, float hi) { unsigned r; asm("v_cvt_pk_bf16_f32 %0, %1, %2" : "=v"(r) : "v"(lo), "v"(hi)); return r; }
; DEVI bf16x8 mk8(uint2 a, uint2 b) { union { uint4 u; bf16x8 v; } c; c.u = make_uint4(a.x, a.y, b.x, b.y); return c.v; }
; template <int DK, bool BIAS> ...
;     ...
;       for (int qi = 0; qi < 2; ++qi) {
;         float mx = -3e38f;
;         if (BIAS) {
; #pragma unroll
;           for (int kt = 0; kt < 4; ++kt) { const f32x4 nf = *(const f32x4*)(fkm + buf * 64 + 16 * kt + 4 * fq);
; #pragma unroll
;             for (int r = 0; r < 4; ++r) { const float t = fmaf(S[kt][qi][r], sc2, nf[r]); S[kt][qi][r] = t; mx = fmaxf(mx, t); } }
;         } else {
; #pragma unroll
;           for (int kt = 0; kt < 4; ++kt)
; #pragma unroll
;             for (int r = 0; r < 4; ++r) mx = fmaxf(mx, S[kt][qi][r]);
;           mx *= sc2;
;         }
;         mx = fmaxf(mx, __shfl_xor(mx, 16)); mx = fmaxf(mx, __shfl_xor(mx, 32));
;         const float mold = mrun[qi], mnew = fmaxf(mold, mx);
;         mrun[qi] = mnew;
;         float ps = 0.f;
; #pragma unroll
;         for (int kt = 0; kt < 4; ++kt)
; #pragma unroll
;           for (int r = 0; r < 4; ++r) { const float pv = BIAS ? __builtin_amdgcn_exp2f(S[kt][qi][r] - mnew) : __builtin_amdgcn_exp2f(fmaf(S[kt][qi][r], sc2, -mnew)); S[kt][qi][r] = pv; ps += pv; }
;         {
;           const float alpha = __builtin_amdgcn_exp2f(mold - mnew);
;           lrun[qi] *= alpha;
; #pragma unroll
;           for (int et = 0; et < 4; ++et) O[et][qi] *= alpha;
;         }
;         lrun[qi] += ps;
; #pragma unroll
;         for (int k2 = 0; k2 < 2; ++k2) { uint2 lo, hi; lo.x = pk_bf16(S[2 * k2][qi][0], S[2 * k2][qi][1]); lo.y = pk_bf16(S[2 * k2][qi][2], S[2 * k2][qi][3]);
;           hi.x = pk_bf16(S[2 * k2 + 1][qi][0], S[2 * k2 + 1][qi][1]); hi.y = pk_bf16(S[2 * k2 + 1][qi][2], S[2 * k2 + 1][qi][3]); pf[qi][k2] = mk8(lo, hi); }
;       }
.LBB0_1797:
	s_or_b64 exec, exec, s[18:19]
	ds_read_b128 v[174:177], v104 offset:37120
	ds_read_b128 v[194:197], v104 offset:37184
	ds_read_b128 v[242:245], v104 offset:37248
	ds_read_b128 v[246:249], v104 offset:37312
	s_mov_b32 s100, 0x3e38aa3b
	s_mov_b32 s101, 0x3e38aa3b
	v_lshlrev_b32_e32 v250, 2, v186
	v_lshlrev_b32_e32 v251, 2, v185
	s_waitcnt lgkmcnt(3)
	v_pk_fma_f32 v[210:211], v[80:81], s[100:101], v[174:175]
	v_pk_fma_f32 v[212:213], v[82:83], s[100:101], v[176:177]
	v_pk_fma_f32 v[226:227], v[64:65], s[100:101], v[174:175]
	v_pk_fma_f32 v[228:229], v[66:67], s[100:101], v[176:177]
	s_waitcnt lgkmcnt(2)
	v_pk_fma_f32 v[214:215], v[86:87], s[100:101], v[194:195]
	v_pk_fma_f32 v[216:217], v[88:89], s[100:101], v[196:197]
	v_pk_fma_f32 v[230:231], v[68:69], s[100:101], v[194:195]
	v_pk_fma_f32 v[232:233], v[70:71], s[100:101], v[196:197]
	s_waitcnt lgkmcnt(1)
	v_pk_fma_f32 v[218:219], v[90:91], s[100:101], v[242:243]
	v_pk_fma_f32 v[220:221], v[92:93], s[100:101], v[244:245]
	v_pk_fma_f32 v[234:235], v[72:73], s[100:101], v[242:243]
	v_pk_fma_f32 v[236:237], v[74:75], s[100:101], v[244:245]
	s_waitcnt lgkmcnt(0)
	v_pk_fma_f32 v[222:223], v[94:95], s[100:101], v[246:247]
	v_pk_fma_f32 v[224:225], v[96:97], s[100:101], v[248:249]
	v_pk_fma_f32 v[238:239], v[76:77], s[100:101], v[246:247]
	v_pk_fma_f32 v[240:241], v[78:79], s[100:101], v[248:249]
	v_max3_f32 v84, v210, s31, v211
	v_max3_f32 v85, v226, s31, v227
	v_max3_f32 v84, v84, v212, v213
	v_max3_f32 v85, v85, v228, v229
	v_max3_f32 v84, v84, v214, v215
	v_max3_f32 v85, v85, v230, v231
	v_max3_f32 v84, v84, v216, v217
	v_max3_f32 v85, v85, v232, v233
	v_max3_f32 v84, v84, v218, v219
	v_max3_f32 v85, v85, v234, v235
	v_max3_f32 v84, v84, v220, v221
	v_max3_f32 v85, v85, v236, v237
	v_max3_f32 v84, v84, v222, v223
	v_max3_f32 v85, v85, v238, v239
	v_max3_f32 v84, v84, v224, v225
	v_max3_f32 v85, v85, v240, v241
	ds_bpermute_b32 v86, v250, v84
	ds_bpermute_b32 v87, v250, v85
	s_waitcnt lgkmcnt(0)
	v_max_f32_e32 v84, v84, v86
	v_max_f32_e32 v85, v85, v87
	ds_bpermute_b32 v86, v251, v84
	ds_bpermute_b32 v87, v251, v85
	s_waitcnt lgkmcnt(0)
	v_max3_f32 v131, v114, v84, v86
	v_max3_f32 v173, v112, v85, v87
	v_sub_f32_e32 v84, v114, v131
	v_sub_f32_e32 v85, v112, v173
	v_exp_f32_e32 v126, v84
	v_exp_f32_e32 v82, v85
	v_sub_f32_e32 v86, 0, v131
	v_sub_f32_e32 v80, 0, v173
	v_pk_add_f32 v[210:211], v[210:211], v[86:87] op_sel_hi:[1,0]
	v_pk_add_f32 v[212:213], v[212:213], v[86:87] op_sel_hi:[1,0]
	v_pk_add_f32 v[226:227], v[226:227], v[80:81] op_sel_hi:[1,0]
	v_pk_add_f32 v[228:229], v[228:229], v[80:81] op_sel_hi:[1,0]
	v_pk_add_f32 v[214:215], v[214:215], v[86:87] op_sel_hi:[1,0]
	v_pk_add_f32 v[216:217], v[216:217], v[86:87] op_sel_hi:[1,0]
	v_pk_add_f32 v[230:231], v[230:231], v[80:81] op_sel_hi:[1,0]
	v_pk_add_f32 v[232:233], v[232:233], v[80:81] op_sel_hi:[1,0]
	v_pk_add_f32 v[218:219], v[218:219], v[86:87] op_sel_hi:[1,0]
	v_pk_add_f32 v[220:221], v[220:221], v[86:87] op_sel_hi:[1,0]
	v_pk_add_f32 v[234:235], v[234:235], v[80:81] op_sel_hi:[1,0]
	v_pk_add_f32 v[236:237], v[236:237], v[80:81] op_sel_hi:[1,0]
	v_pk_add_f32 v[222:223], v[222:223], v[86:87] op_sel_hi:[1,0]
	v_pk_add_f32 v[224:225], v[224:225], v[86:87] op_sel_hi:[1,0]
	v_pk_add_f32 v[238:239], v[238:239], v[80:81] op_sel_hi:[1,0]
	v_pk_add_f32 v[240:241], v[240:241], v[80:81] op_sel_hi:[1,0]
	v_exp_f32_e32 v155, v210
	v_exp_f32_e32 v154, v226
	v_exp_f32_e32 v157, v211
	v_exp_f32_e32 v156, v227
	v_exp_f32_e32 v151, v212
	v_exp_f32_e32 v150, v228
	v_exp_f32_e32 v153, v213
	v_exp_f32_e32 v152, v229
	v_exp_f32_e32 v117, v214
	v_exp_f32_e32 v116, v230
	v_exp_f32_e32 v119, v215
	v_exp_f32_e32 v118, v231
	v_exp_f32_e32 v123, v216
	v_exp_f32_e32 v122, v232
	v_exp_f32_e32 v121, v217
	v_exp_f32_e32 v120, v233
	v_exp_f32_e32 v125, v218
	v_exp_f32_e32 v124, v234
	v_exp_f32_e32 v89, v219
	v_exp_f32_e32 v88, v235
	v_exp_f32_e32 v95, v220
	v_exp_f32_e32 v94, v236
	v_exp_f32_e32 v115, v221
	v_exp_f32_e32 v114, v237
	v_exp_f32_e32 v93, v222
	v_exp_f32_e32 v92, v238
	v_exp_f32_e32 v113, v223
	v_exp_f32_e32 v112, v239
	v_exp_f32_e32 v91, v224
	v_exp_f32_e32 v90, v240
	v_exp_f32_e32 v97, v225
	v_exp_f32_e32 v96, v241
	v_pk_mul_f32 v[202:203], v[52:53], v[126:127] op_sel_hi:[1,0]
	v_pk_mul_f32 v[52:53], v[56:57], v[126:127] op_sel_hi:[1,0]
	v_pk_mul_f32 v[198:199], v[48:49], v[126:127] op_sel_hi:[1,0]
	v_pk_mul_f32 v[48:49], v[60:61], v[126:127] op_sel_hi:[1,0]
	v_add_u32_e32 v174, 0x6800, v170
	v_add_u32_e32 v175, 0x7000, v170
	v_pk_mul_f32 v[200:201], v[50:51], v[126:127] op_sel_hi:[1,0]
	v_add_u32_e32 v176, 0x7800, v170
	v_pk_mul_f32 v[204:205], v[54:55], v[126:127] op_sel_hi:[1,0]
	v_pk_add_f32 v[64:65], v[154:155], 0 op_sel_hi:[1,0]
	v_pk_add_f32 v[80:81], v[156:157], v[64:65]
	ds_read2_b64 v[64:67], v174 offset0:128 offset1:132
	ds_read2_b64 v[72:75], v175 offset0:160 offset1:164
	v_pk_mul_f32 v[46:47], v[46:47], v[82:83] op_sel_hi:[1,0]
	v_pk_mul_f32 v[44:45], v[44:45], v[82:83] op_sel_hi:[1,0]
	v_pk_mul_f32 v[54:55], v[58:59], v[126:127] op_sel_hi:[1,0]
	v_cvt_pk_bf16_f32 v56, v155, v157
	v_cvt_pk_bf16_f32 v57, v151, v153
	v_cvt_pk_bf16_f32 v58, v117, v119
	v_cvt_pk_bf16_f32 v59, v123, v121
	v_cvt_pk_bf16_f32 v68, v154, v156
	s_waitcnt lgkmcnt(1)
; DEVI unsigned pk_bf16(float lo, float hi) { unsigned r; asm("v_cvt_pk_bf16_f32 %0, %1, %2" : "=v"(r) : "v"(lo), "v"(hi)); return r; }
; DEVI bf16x8 mk8(uint2 a, uint2 b) { union { uint4 u; bf16x8 v; } c; c.u = make_uint4(a.x, a.y, b.x, b.y); return c.v; }
; #define MFMA(a, b, c) __builtin_amdgcn_mfma_f32_16x16x32_bf16((a), (b), (c), 0, 0, 0)
; template <int DK, bool BIAS> ...
;     ...
;         {
;           const float alpha = __builtin_amdgcn_exp2f(mold - mnew);
;           lrun[qi] *= alpha;
; #pragma unroll
;           for (int et = 0; et < 4; ++et) O[et][qi] *= alpha;
;         }
;         lrun[qi] += ps;
; #pragma unroll
;         for (int k2 = 0; k2 < 2; ++k2) { uint2 lo, hi; lo.x = pk_bf16(S[2 * k2][qi][0], S[2 * k2][qi][1]); lo.y = pk_bf16(S[2 * k2][qi][2], S[2 * k2][qi][3]);
;           hi.x = pk_bf16(S[2 * k2 + 1][qi][0], S[2 * k2 + 1][qi][1]); hi.y = pk_bf16(S[2 * k2 + 1][qi][2], S[2 * k2 + 1][qi][3]); pf[qi][k2] = mk8(lo, hi); }
;       }
; #pragma unroll
;       for (int k2 = 0; k2 < 2; ++k2)
; #pragma unroll
;         for (int et = 0; et < 4; ++et) {
;           const uint2 v0 = *(const uint2*)(Vtm + (buf * 64 + 16 * et + fr) * 72 + 32 * k2 + 4 * fq), v1 = *(const uint2*)(Vtm + (buf * 64 + 16 * et + fr) * 72 + 32 * k2 + 16 + 4 * fq);
;           const bf16x8 va = mk8(v0, v1);
; #pragma unroll
;           for (int qi = 0; qi < 2; ++qi) O[et][qi] = MFMA(va, pf[qi][k2], O[et][qi]);
;         }
	v_mfma_f32_16x16x32_bf16 v[76:79], v[64:67], v[56:59], v[198:201]
	v_cvt_pk_bf16_f32 v69, v150, v152
	v_cvt_pk_bf16_f32 v70, v116, v118
	v_cvt_pk_bf16_f32 v71, v122, v120
	v_mul_f32_e64 v42, v42, v82
	v_mul_f32_e64 v43, v43, v82
	v_mfma_f32_16x16x32_bf16 v[44:47], v[64:67], v[68:71], v[44:47]
	ds_read2_b64 v[64:67], v176 offset0:192 offset1:196
	v_pk_mul_f32 v[40:41], v[40:41], v[82:83] op_sel_hi:[1,0]
	v_add_u32_e32 v177, 0x8000, v170
	s_waitcnt lgkmcnt(1)
	v_mfma_f32_16x16x32_bf16 v[84:87], v[72:75], v[56:59], v[202:205]
	v_pk_mul_f32 v[50:51], v[62:63], v[126:127] op_sel_hi:[1,0]
	v_mfma_f32_16x16x32_bf16 v[40:43], v[72:75], v[68:71], v[40:43]
	ds_read2_b64 v[72:75], v177 offset0:224 offset1:228
	v_pk_mul_f32 v[38:39], v[38:39], v[82:83] op_sel_hi:[1,0]
	v_pk_mul_f32 v[36:37], v[36:37], v[82:83] op_sel_hi:[1,0]
	s_waitcnt lgkmcnt(1)
	v_mfma_f32_16x16x32_bf16 v[154:157], v[64:67], v[56:59], v[52:55]
	v_mul_f32_e64 v34, v34, v82
	v_mul_f32_e64 v35, v35, v82
	v_pk_mul_f32 v[32:33], v[32:33], v[82:83] op_sel_hi:[1,0]
	v_cvt_pk_bf16_f32 v60, v125, v89
	v_mfma_f32_16x16x32_bf16 v[36:39], v[64:67], v[68:71], v[36:39]
	ds_read2_b64 v[52:55], v174 offset0:136 offset1:140
	s_waitcnt lgkmcnt(1)
	v_mfma_f32_16x16x32_bf16 v[64:67], v[72:75], v[56:59], v[48:51]
	ds_read2_b64 v[56:59], v175 offset0:168 offset1:172
	v_cvt_pk_bf16_f32 v61, v95, v115
	v_cvt_pk_bf16_f32 v62, v93, v113
	v_cvt_pk_bf16_f32 v63, v91, v97
	s_nop 0
	v_mfma_f32_16x16x32_bf16 v[32:35], v[72:75], v[68:71], v[32:35]
	v_cvt_pk_bf16_f32 v68, v124, v88
	v_cvt_pk_bf16_f32 v69, v94, v114
	s_waitcnt lgkmcnt(1)
	v_mfma_f32_16x16x32_bf16 v[48:51], v[52:55], v[60:63], v[76:79]
	v_cvt_pk_bf16_f32 v70, v92, v112
	v_cvt_pk_bf16_f32 v71, v90, v96
	ds_read2_b64 v[72:75], v176 offset0:200 offset1:204
	s_nop 0
	v_mfma_f32_16x16x32_bf16 v[44:47], v[52:55], v[68:71], v[44:47]
	v_add_f32_e64 v52, v150, v80
	v_add_f32_e64 v53, v151, v81
	v_mov_b32_e32 v83, v126
	v_pk_add_f32 v[76:77], v[152:153], v[52:53]
	s_waitcnt lgkmcnt(1)
	v_mfma_f32_16x16x32_bf16 v[52:55], v[56:59], v[60:63], v[84:87]
	v_add_f32_e64 v76, v116, v76
	v_add_f32_e64 v77, v117, v77
	v_pk_add_f32 v[76:77], v[118:119], v[76:77]
	v_mfma_f32_16x16x32_bf16 v[40:43], v[56:59], v[68:71], v[40:43]
	v_add_f32_e64 v76, v122, v76
	v_add_f32_e64 v77, v123, v77
	v_pk_add_f32 v[56:57], v[120:121], v[76:77]
	ds_read2_b64 v[76:79], v177 offset0:232 offset1:236
	v_pk_add_f32 v[80:81], v[124:125], v[56:57]
	s_waitcnt lgkmcnt(1)
	v_mfma_f32_16x16x32_bf16 v[56:59], v[72:75], v[60:63], v[154:157]
	v_add_f32_e64 v80, v88, v80
	v_add_f32_e64 v81, v89, v81
	v_pk_add_f32 v[80:81], v[94:95], v[80:81]
	v_mfma_f32_16x16x32_bf16 v[36:39], v[72:75], v[68:71], v[36:39]
	v_add_f32_e64 v80, v114, v80
	v_add_f32_e64 v81, v115, v81
	v_mov_b32_e32 v114, v131
	v_pk_add_f32 v[72:73], v[92:93], v[80:81]
	s_waitcnt lgkmcnt(0)
	v_mfma_f32_16x16x32_bf16 v[60:63], v[76:79], v[60:63], v[64:67]
	v_add_f32_e64 v72, v112, v72
	v_add_f32_e64 v73, v113, v73
	v_mov_b32_e32 v112, v173
	v_mfma_f32_16x16x32_bf16 v[32:35], v[76:79], v[68:71], v[32:35]
	v_add_f32_e64 v64, v90, v72
	v_add_f32_e64 v65, v91, v73
	v_pk_add_f32 v[64:65], v[96:97], v[64:65]
	s_nop 0
	v_pk_fma_f32 v[106:107], v[106:107], v[82:83], v[64:65]

; DEVI unsigned pk_bf16(float lo, float hi) { unsigned r; asm("v_cvt_pk_bf16_f32 %0, %1, %2" : "=v"(r) : "v"(lo), "v"(hi)); return r; }
; DEVI bf16x8 mk8(uint2 a, uint2 b) { union { uint4 u; bf16x8 v; } c; c.u = make_uint4(a.x, a.y, b.x, b.y); return c.v; }
; template <int DK, bool BIAS> ...
;     ...
;       for (int qi = 0; qi < 2; ++qi) {
;         float mx = -3e38f;
;         if (BIAS) {
; #pragma unroll
;           for (int kt = 0; kt < 4; ++kt) { const f32x4 nf = *(const f32x4*)(fkm + buf * 64 + 16 * kt + 4 * fq);
; #pragma unroll
;             for (int r = 0; r < 4; ++r) { const float t = fmaf(S[kt][qi][r], sc2, nf[r]); S[kt][qi][r] = t; mx = fmaxf(mx, t); } }
;         } else {
; #pragma unroll
;           for (int kt = 0; kt < 4; ++kt)
; #pragma unroll
;             for (int r = 0; r < 4; ++r) mx = fmaxf(mx, S[kt][qi][r]);
;           mx *= sc2;
;         }
;         mx = fmaxf(mx, __shfl_xor(mx, 16)); mx = fmaxf(mx, __shfl_xor(mx, 32));
;         const float mold = mrun[qi], mnew = fmaxf(mold, mx);
;         mrun[qi] = mnew;
;         float ps = 0.f;
; #pragma unroll
;         for (int kt = 0; kt < 4; ++kt)
; #pragma unroll
;           for (int r = 0; r < 4; ++r) { const float pv = BIAS ? __builtin_amdgcn_exp2f(S[kt][qi][r] - mnew) : __builtin_amdgcn_exp2f(fmaf(S[kt][qi][r], sc2, -mnew)); S[kt][qi][r] = pv; ps += pv; }
;         {
;           const float alpha = __builtin_amdgcn_exp2f(mold - mnew);
;           lrun[qi] *= alpha;
; #pragma unroll
;           for (int et = 0; et < 4; ++et) O[et][qi] *= alpha;
;         }
;         lrun[qi] += ps;
; #pragma unroll
;         for (int k2 = 0; k2 < 2; ++k2) { uint2 lo, hi; lo.x = pk_bf16(S[2 * k2][qi][0], S[2 * k2][qi][1]); lo.y = pk_bf16(S[2 * k2][qi][2], S[2 * k2][qi][3]);
;           hi.x = pk_bf16(S[2 * k2 + 1][qi][0], S[2 * k2 + 1][qi][1]); hi.y = pk_bf16(S[2 * k2 + 1][qi][2], S[2 * k2 + 1][qi][3]); pf[qi][k2] = mk8(lo, hi); }
;       }
.LBB0_1866:
	s_or_b64 exec, exec, s[18:19]
	s_mov_b32 s100, s34
	s_mov_b32 s101, s34
	v_lshlrev_b32_e32 v250, 2, v186
	v_lshlrev_b32_e32 v251, 2, v185
	v_max3_f32 v242, v96, s31, v97
	v_max3_f32 v243, v84, s31, v85
	v_max3_f32 v242, v242, v98, v99
	v_max3_f32 v243, v243, v86, v87
	v_max3_f32 v242, v242, v100, v101
	v_max3_f32 v243, v243, v88, v89
	v_max3_f32 v242, v242, v102, v103
	v_max3_f32 v243, v243, v90, v91
	v_max3_f32 v242, v242, v104, v105
	v_max3_f32 v243, v243, v80, v81
	v_max3_f32 v242, v242, v106, v107
	v_max3_f32 v243, v243, v82, v83
	v_max3_f32 v242, v242, v108, v109
	v_max3_f32 v243, v243, v92, v93
	v_max3_f32 v242, v242, v110, v111
	v_max3_f32 v243, v243, v94, v95
	v_mul_f32_e32 v242, 0x3e16c740, v242
	v_mul_f32_e32 v243, 0x3e16c740, v243
	ds_bpermute_b32 v244, v250, v242
	ds_bpermute_b32 v245, v250, v243
	s_waitcnt lgkmcnt(0)
	v_max_f32_e32 v242, v242, v244
	v_max_f32_e32 v243, v243, v245
	ds_bpermute_b32 v244, v251, v242
	ds_bpermute_b32 v245, v251, v243
	s_waitcnt lgkmcnt(0)
	v_max3_f32 v131, v154, v242, v244
	v_max3_f32 v209, v208, v243, v245
	v_sub_f32_e32 v242, v154, v131
	v_sub_f32_e32 v243, v208, v209
	v_sub_f32_e32 v246, 0, v131
	v_sub_f32_e32 v248, 0, v209
	v_pk_fma_f32 v[210:211], v[96:97], s[100:101], v[246:247] op_sel_hi:[1,1,0]
	v_pk_fma_f32 v[226:227], v[80:81], s[100:101], v[248:249] op_sel_hi:[1,1,0]
	v_pk_fma_f32 v[212:213], v[98:99], s[100:101], v[246:247] op_sel_hi:[1,1,0]
	v_pk_fma_f32 v[228:229], v[82:83], s[100:101], v[248:249] op_sel_hi:[1,1,0]
	v_pk_fma_f32 v[214:215], v[100:101], s[100:101], v[246:247] op_sel_hi:[1,1,0]
	v_pk_fma_f32 v[230:231], v[84:85], s[100:101], v[248:249] op_sel_hi:[1,1,0]
	v_pk_fma_f32 v[216:217], v[102:103], s[100:101], v[246:247] op_sel_hi:[1,1,0]
	v_pk_fma_f32 v[232:233], v[86:87], s[100:101], v[248:249] op_sel_hi:[1,1,0]
	v_pk_fma_f32 v[218:219], v[104:105], s[100:101], v[246:247] op_sel_hi:[1,1,0]
	v_pk_fma_f32 v[234:235], v[88:89], s[100:101], v[248:249] op_sel_hi:[1,1,0]
	v_pk_fma_f32 v[220:221], v[106:107], s[100:101], v[246:247] op_sel_hi:[1,1,0]
	v_pk_fma_f32 v[236:237], v[90:91], s[100:101], v[248:249] op_sel_hi:[1,1,0]
	v_pk_fma_f32 v[222:223], v[108:109], s[100:101], v[246:247] op_sel_hi:[1,1,0]
	v_pk_fma_f32 v[238:239], v[92:93], s[100:101], v[248:249] op_sel_hi:[1,1,0]
	v_pk_fma_f32 v[224:225], v[110:111], s[100:101], v[246:247] op_sel_hi:[1,1,0]
	v_pk_fma_f32 v[240:241], v[94:95], s[100:101], v[248:249] op_sel_hi:[1,1,0]
	v_exp_f32_e32 v178, v242
	v_exp_f32_e32 v90, v243
	v_exp_f32_e32 v163, v210
	v_exp_f32_e32 v170, v226
	v_exp_f32_e32 v165, v211
	v_exp_f32_e32 v104, v227
	v_exp_f32_e32 v167, v212
	v_exp_f32_e32 v172, v228
	v_exp_f32_e32 v169, v213
	v_exp_f32_e32 v106, v229
	v_exp_f32_e32 v155, v214
	v_exp_f32_e32 v162, v230
	v_exp_f32_e32 v157, v215
	v_exp_f32_e32 v164, v231
	v_exp_f32_e32 v159, v216
	v_exp_f32_e32 v166, v232
	v_exp_f32_e32 v161, v217
	v_exp_f32_e32 v168, v233
	v_exp_f32_e32 v171, v218
	v_exp_f32_e32 v154, v234
	v_exp_f32_e32 v105, v219
	v_exp_f32_e32 v156, v235
	v_exp_f32_e32 v173, v220
	v_exp_f32_e32 v158, v236
	v_exp_f32_e32 v107, v221
	v_exp_f32_e32 v160, v237
	v_exp_f32_e32 v175, v222
	v_exp_f32_e32 v174, v238
	v_exp_f32_e32 v109, v223
	v_exp_f32_e32 v108, v239
	v_exp_f32_e32 v177, v224
	v_exp_f32_e32 v176, v240
	v_exp_f32_e32 v111, v225
	v_exp_f32_e32 v110, v241
	v_pk_add_f32 v[80:81], v[154:155], 0 op_sel_hi:[1,0]
	v_pk_add_f32 v[80:81], v[156:157], v[80:81]
	v_pk_add_f32 v[80:81], v[158:159], v[80:81]
	v_pk_add_f32 v[80:81], v[160:161], v[80:81]
	v_pk_add_f32 v[80:81], v[162:163], v[80:81]
	v_pk_mul_f32 v[102:103], v[66:67], v[178:179] op_sel_hi:[1,0]
	v_pk_add_f32 v[80:81], v[164:165], v[80:81]
	v_pk_mul_f32 v[100:101], v[64:65], v[178:179] op_sel_hi:[1,0]
	v_pk_add_f32 v[80:81], v[166:167], v[80:81]
	v_pk_mul_f32 v[64:65], v[76:77], v[178:179] op_sel_hi:[1,0]
	v_pk_add_f32 v[80:81], v[168:169], v[80:81]
	v_cvt_pk_bf16_f32 v76, v171, v105
	v_pk_mul_f32 v[98:99], v[70:71], v[178:179] op_sel_hi:[1,0]
	v_pk_add_f32 v[80:81], v[170:171], v[80:81]
	v_pk_mul_f32 v[96:97], v[68:69], v[178:179] op_sel_hi:[1,0]
	v_pk_add_f32 v[88:89], v[104:105], v[80:81]
	v_add_u32_e32 v105, 0x7000, v203
	v_cvt_pk_bf16_f32 v68, v155, v157
	v_cvt_pk_bf16_f32 v69, v159, v161
	v_pk_mul_f32 v[84:85], v[52:53], v[90:91] op_sel_hi:[1,0]
	v_pk_add_f32 v[52:53], v[172:173], v[88:89]
	v_pk_mul_f32 v[82:83], v[50:51], v[90:91] op_sel_hi:[1,0]
	v_pk_add_f32 v[52:53], v[106:107], v[52:53]
	v_pk_mul_f32 v[80:81], v[48:49], v[90:91] op_sel_hi:[1,0]
	v_pk_add_f32 v[52:53], v[174:175], v[52:53]
	v_pk_mul_f32 v[86:87], v[54:55], v[90:91] op_sel_hi:[1,0]
	v_pk_add_f32 v[52:53], v[108:109], v[52:53]
	v_pk_mul_f32 v[58:59], v[58:59], v[90:91] op_sel_hi:[1,0]
	v_pk_add_f32 v[52:53], v[176:177], v[52:53]
	v_pk_mul_f32 v[56:57], v[56:57], v[90:91] op_sel_hi:[1,0]
	v_pk_mul_f32 v[50:51], v[62:63], v[90:91] op_sel_hi:[1,0]
	v_pk_mul_f32 v[48:49], v[60:61], v[90:91] op_sel_hi:[1,0]
	v_mov_b32_e32 v91, v178
	v_pk_add_f32 v[52:53], v[110:111], v[52:53]
	v_cvt_pk_bf16_f32 v60, v170, v104
	v_add_u32_e32 v104, 0x6800, v203
	v_pk_fma_f32 v[120:121], v[120:121], v[90:91], v[52:53]
	ds_read2_b64 v[88:91], v104 offset1:4
	v_cvt_pk_bf16_f32 v70, v163, v165
	v_cvt_pk_bf16_f32 v71, v167, v169
	v_cvt_pk_bf16_f32 v52, v154, v156
	v_cvt_pk_bf16_f32 v53, v158, v160
	v_cvt_pk_bf16_f32 v54, v162, v164
	v_cvt_pk_bf16_f32 v55, v166, v168
	v_cvt_pk_bf16_f32 v61, v172, v106
	s_waitcnt lgkmcnt(0)
; DEVI unsigned pk_bf16(float lo, float hi) { unsigned r; asm("v_cvt_pk_bf16_f32 %0, %1, %2" : "=v"(r) : "v"(lo), "v"(hi)); return r; }
; DEVI bf16x8 mk8(uint2 a, uint2 b) { union { uint4 u; bf16x8 v; } c; c.u = make_uint4(a.x, a.y, b.x, b.y); return c.v; }
; #define MFMA(a, b, c) __builtin_amdgcn_mfma_f32_16x16x32_bf16((a), (b), (c), 0, 0, 0)
; template <int DK, bool BIAS> ...
;     ...
;         {
;           const float alpha = __builtin_amdgcn_exp2f(mold - mnew);
;           lrun[qi] *= alpha;
; #pragma unroll
;           for (int et = 0; et < 4; ++et) O[et][qi] *= alpha;
;         }
;         lrun[qi] += ps;
; #pragma unroll
;         for (int k2 = 0; k2 < 2; ++k2) { uint2 lo, hi; lo.x = pk_bf16(S[2 * k2][qi][0], S[2 * k2][qi][1]); lo.y = pk_bf16(S[2 * k2][qi][2], S[2 * k2][qi][3]);
;           hi.x = pk_bf16(S[2 * k2 + 1][qi][0], S[2 * k2 + 1][qi][1]); hi.y = pk_bf16(S[2 * k2 + 1][qi][2], S[2 * k2 + 1][qi][3]); pf[qi][k2] = mk8(lo, hi); }
;       }
; #pragma unroll
;       for (int k2 = 0; k2 < 2; ++k2)
; #pragma unroll
;         for (int et = 0; et < 4; ++et) {
;           const uint2 v0 = *(const uint2*)(Vtm + (buf * 64 + 16 * et + fr) * 72 + 32 * k2 + 4 * fq), v1 = *(const uint2*)(Vtm + (buf * 64 + 16 * et + fr) * 72 + 32 * k2 + 16 + 4 * fq);
;           const bf16x8 va = mk8(v0, v1);
; #pragma unroll
;           for (int qi = 0; qi < 2; ++qi) O[et][qi] = MFMA(va, pf[qi][k2], O[et][qi]);
;         }
	v_mfma_f32_16x16x32_bf16 v[92:95], v[88:91], v[68:71], v[100:103]
	v_add_u32_e32 v106, 0x7800, v203
	v_pk_mul_f32 v[74:75], v[74:75], v[178:179] op_sel_hi:[1,0]
	v_pk_mul_f32 v[72:73], v[72:73], v[178:179] op_sel_hi:[1,0]
	v_mfma_f32_16x16x32_bf16 v[80:83], v[88:91], v[52:55], v[80:83]
	ds_read2_b64 v[88:91], v105 offset0:32 offset1:36
	v_cvt_pk_bf16_f32 v77, v173, v107
	v_add_u32_e32 v107, 0x8000, v203
	s_waitcnt lgkmcnt(0)
	v_mfma_f32_16x16x32_bf16 v[96:99], v[88:91], v[68:71], v[96:99]
	v_mul_f32_e64 v66, v78, v178
	v_mul_f32_e64 v67, v79, v178
	v_cvt_pk_bf16_f32 v78, v175, v109
	v_cvt_pk_bf16_f32 v79, v177, v111
	v_mfma_f32_16x16x32_bf16 v[84:87], v[88:91], v[52:55], v[84:87]
	ds_read2_b64 v[88:91], v106 offset0:64 offset1:68
	v_cvt_pk_bf16_f32 v62, v174, v108
	v_cvt_pk_bf16_f32 v63, v176, v110
	s_waitcnt lgkmcnt(0)
	v_mfma_f32_16x16x32_bf16 v[72:75], v[88:91], v[68:71], v[72:75]
	v_mov_b32_e32 v208, v209
	v_mov_b32_e32 v154, v131
	v_mfma_f32_16x16x32_bf16 v[56:59], v[88:91], v[52:55], v[56:59]
	ds_read2_b64 v[88:91], v107 offset0:96 offset1:100
	s_waitcnt lgkmcnt(0)
	v_mfma_f32_16x16x32_bf16 v[100:103], v[88:91], v[68:71], v[64:67]
	v_mfma_f32_16x16x32_bf16 v[88:91], v[88:91], v[52:55], v[48:51]
	ds_read2_b64 v[52:55], v105 offset0:40 offset1:44
	s_nop 1
	ds_read2_b64 v[48:51], v104 offset0:8 offset1:12
	s_waitcnt lgkmcnt(0)
	v_mfma_f32_16x16x32_bf16 v[64:67], v[48:51], v[76:79], v[92:95]
	v_mfma_f32_16x16x32_bf16 v[48:51], v[48:51], v[60:63], v[80:83]
	s_nop 2
	ds_read2_b64 v[80:83], v106 offset0:72 offset1:76
	s_waitcnt lgkmcnt(0)
	v_mfma_f32_16x16x32_bf16 v[72:75], v[80:83], v[76:79], v[72:75]
	v_mfma_f32_16x16x32_bf16 v[56:59], v[80:83], v[60:63], v[56:59]
	ds_read2_b64 v[80:83], v107 offset0:104 offset1:108
	v_mfma_f32_16x16x32_bf16 v[68:71], v[52:55], v[76:79], v[96:99]
	v_mfma_f32_16x16x32_bf16 v[52:55], v[52:55], v[60:63], v[84:87]
	s_waitcnt lgkmcnt(0)
	v_mfma_f32_16x16x32_bf16 v[76:79], v[80:83], v[76:79], v[100:103]
	v_mfma_f32_16x16x32_bf16 v[60:63], v[80:83], v[60:63], v[88:91]

; DEVI unsigned pk_bf16(float lo, float hi) { unsigned r; asm("v_cvt_pk_bf16_f32 %0, %1, %2" : "=v"(r) : "v"(lo), "v"(hi)); return r; }
; DEVI bf16x8 mk8(uint2 a, uint2 b) { union { uint4 u; bf16x8 v; } c; c.u = make_uint4(a.x, a.y, b.x, b.y); return c.v; }
; template <int DK, bool BIAS> ...
;     ...
;       for (int qi = 0; qi < 2; ++qi) {
;         float mx = -3e38f;
;         if (BIAS) {
; #pragma unroll
;           for (int kt = 0; kt < 4; ++kt) { const f32x4 nf = *(const f32x4*)(fkm + buf * 64 + 16 * kt + 4 * fq);
; #pragma unroll
;             for (int r = 0; r < 4; ++r) { const float t = fmaf(S[kt][qi][r], sc2, nf[r]); S[kt][qi][r] = t; mx = fmaxf(mx, t); } }
;         } else {
; #pragma unroll
;           for (int kt = 0; kt < 4; ++kt)
; #pragma unroll
;             for (int r = 0; r < 4; ++r) mx = fmaxf(mx, S[kt][qi][r]);
;           mx *= sc2;
;         }
;         mx = fmaxf(mx, __shfl_xor(mx, 16)); mx = fmaxf(mx, __shfl_xor(mx, 32));
;         const float mold = mrun[qi], mnew = fmaxf(mold, mx);
;         mrun[qi] = mnew;
;         float ps = 0.f;
; #pragma unroll
;         for (int kt = 0; kt < 4; ++kt)
; #pragma unroll
;           for (int r = 0; r < 4; ++r) { const float pv = BIAS ? __builtin_amdgcn_exp2f(S[kt][qi][r] - mnew) : __builtin_amdgcn_exp2f(fmaf(S[kt][qi][r], sc2, -mnew)); S[kt][qi][r] = pv; ps += pv; }
;         {
;           const float alpha = __builtin_amdgcn_exp2f(mold - mnew);
;           lrun[qi] *= alpha;
; #pragma unroll
;           for (int et = 0; et < 4; ++et) O[et][qi] *= alpha;
;         }
;         lrun[qi] += ps;
; #pragma unroll
;         for (int k2 = 0; k2 < 2; ++k2) { uint2 lo, hi; lo.x = pk_bf16(S[2 * k2][qi][0], S[2 * k2][qi][1]); lo.y = pk_bf16(S[2 * k2][qi][2], S[2 * k2][qi][3]);
;           hi.x = pk_bf16(S[2 * k2 + 1][qi][0], S[2 * k2 + 1][qi][1]); hi.y = pk_bf16(S[2 * k2 + 1][qi][2], S[2 * k2 + 1][qi][3]); pf[qi][k2] = mk8(lo, hi); }
;       }
.LBB0_1888:
	s_or_b64 exec, exec, s[18:19]
	s_mov_b32 s100, s34
	s_mov_b32 s101, s34
	v_lshlrev_b32_e32 v250, 2, v186
	v_lshlrev_b32_e32 v251, 2, v185
	v_max3_f32 v242, v96, s31, v97
	v_max3_f32 v243, v84, s31, v85
	v_max3_f32 v242, v242, v98, v99
	v_max3_f32 v243, v243, v86, v87
	v_max3_f32 v242, v242, v100, v101
	v_max3_f32 v243, v243, v88, v89
	v_max3_f32 v242, v242, v102, v103
	v_max3_f32 v243, v243, v90, v91
	v_max3_f32 v242, v242, v104, v105
	v_max3_f32 v243, v243, v80, v81
	v_max3_f32 v242, v242, v106, v107
	v_max3_f32 v243, v243, v82, v83
	v_max3_f32 v242, v242, v108, v109
	v_max3_f32 v243, v243, v92, v93
	v_max3_f32 v242, v242, v110, v111
	v_max3_f32 v243, v243, v94, v95
	v_mul_f32_e32 v242, 0x3e16c740, v242
	v_mul_f32_e32 v243, 0x3e16c740, v243
	ds_bpermute_b32 v244, v250, v242
	ds_bpermute_b32 v245, v250, v243
	s_waitcnt lgkmcnt(0)
	v_max_f32_e32 v242, v242, v244
	v_max_f32_e32 v243, v243, v245
	ds_bpermute_b32 v244, v251, v242
	ds_bpermute_b32 v245, v251, v243
	s_waitcnt lgkmcnt(0)
	v_max3_f32 v131, v154, v242, v244
	v_max3_f32 v209, v208, v243, v245
	v_sub_f32_e32 v242, v154, v131
	v_sub_f32_e32 v243, v208, v209
	v_sub_f32_e32 v246, 0, v131
	v_sub_f32_e32 v248, 0, v209
	v_pk_fma_f32 v[210:211], v[96:97], s[100:101], v[246:247] op_sel_hi:[1,1,0]
	v_pk_fma_f32 v[226:227], v[80:81], s[100:101], v[248:249] op_sel_hi:[1,1,0]
	v_pk_fma_f32 v[212:213], v[98:99], s[100:101], v[246:247] op_sel_hi:[1,1,0]
	v_pk_fma_f32 v[228:229], v[82:83], s[100:101], v[248:249] op_sel_hi:[1,1,0]
	v_pk_fma_f32 v[214:215], v[100:101], s[100:101], v[246:247] op_sel_hi:[1,1,0]
	v_pk_fma_f32 v[230:231], v[84:85], s[100:101], v[248:249] op_sel_hi:[1,1,0]
	v_pk_fma_f32 v[216:217], v[102:103], s[100:101], v[246:247] op_sel_hi:[1,1,0]
	v_pk_fma_f32 v[232:233], v[86:87], s[100:101], v[248:249] op_sel_hi:[1,1,0]
	v_pk_fma_f32 v[218:219], v[104:105], s[100:101], v[246:247] op_sel_hi:[1,1,0]
	v_pk_fma_f32 v[234:235], v[88:89], s[100:101], v[248:249] op_sel_hi:[1,1,0]
	v_pk_fma_f32 v[220:221], v[106:107], s[100:101], v[246:247] op_sel_hi:[1,1,0]
	v_pk_fma_f32 v[236:237], v[90:91], s[100:101], v[248:249] op_sel_hi:[1,1,0]
	v_pk_fma_f32 v[222:223], v[108:109], s[100:101], v[246:247] op_sel_hi:[1,1,0]
	v_pk_fma_f32 v[238:239], v[92:93], s[100:101], v[248:249] op_sel_hi:[1,1,0]
	v_pk_fma_f32 v[224:225], v[110:111], s[100:101], v[246:247] op_sel_hi:[1,1,0]
	v_pk_fma_f32 v[240:241], v[94:95], s[100:101], v[248:249] op_sel_hi:[1,1,0]
	v_exp_f32_e32 v178, v242
	v_exp_f32_e32 v90, v243
	v_exp_f32_e32 v163, v210
	v_exp_f32_e32 v162, v226
	v_exp_f32_e32 v165, v211
	v_exp_f32_e32 v164, v227
	v_exp_f32_e32 v167, v212
	v_exp_f32_e32 v166, v228
	v_exp_f32_e32 v169, v213
	v_exp_f32_e32 v168, v229
	v_exp_f32_e32 v155, v214
	v_exp_f32_e32 v170, v230
	v_exp_f32_e32 v157, v215
	v_exp_f32_e32 v104, v231
	v_exp_f32_e32 v159, v216
	v_exp_f32_e32 v172, v232
	v_exp_f32_e32 v161, v217
	v_exp_f32_e32 v106, v233
	v_exp_f32_e32 v171, v218
	v_exp_f32_e32 v154, v234
	v_exp_f32_e32 v105, v219
	v_exp_f32_e32 v156, v235
	v_exp_f32_e32 v173, v220
	v_exp_f32_e32 v158, v236
	v_exp_f32_e32 v107, v221
	v_exp_f32_e32 v160, v237
	v_exp_f32_e32 v175, v222
	v_exp_f32_e32 v174, v238
	v_exp_f32_e32 v109, v223
	v_exp_f32_e32 v108, v239
	v_exp_f32_e32 v177, v224
	v_exp_f32_e32 v176, v240
	v_exp_f32_e32 v111, v225
	v_exp_f32_e32 v110, v241
	v_pk_add_f32 v[80:81], v[154:155], 0 op_sel_hi:[1,0]
	v_pk_add_f32 v[80:81], v[156:157], v[80:81]
	v_pk_mul_f32 v[102:103], v[66:67], v[178:179] op_sel_hi:[1,0]
	v_pk_add_f32 v[80:81], v[158:159], v[80:81]
	v_pk_mul_f32 v[100:101], v[64:65], v[178:179] op_sel_hi:[1,0]
	v_pk_add_f32 v[80:81], v[160:161], v[80:81]
	v_pk_mul_f32 v[64:65], v[76:77], v[178:179] op_sel_hi:[1,0]
	v_pk_add_f32 v[80:81], v[162:163], v[80:81]
	v_cvt_pk_bf16_f32 v76, v171, v105
	v_pk_mul_f32 v[98:99], v[70:71], v[178:179] op_sel_hi:[1,0]
	v_pk_add_f32 v[80:81], v[164:165], v[80:81]
	v_pk_mul_f32 v[96:97], v[68:69], v[178:179] op_sel_hi:[1,0]
	v_pk_add_f32 v[88:89], v[166:167], v[80:81]
	v_cvt_pk_bf16_f32 v68, v155, v157
	v_cvt_pk_bf16_f32 v69, v159, v161
	v_cvt_pk_bf16_f32 v70, v163, v165
	v_cvt_pk_bf16_f32 v71, v167, v169
	v_pk_mul_f32 v[74:75], v[74:75], v[178:179] op_sel_hi:[1,0]
	v_pk_mul_f32 v[84:85], v[52:53], v[90:91] op_sel_hi:[1,0]
	v_pk_add_f32 v[52:53], v[168:169], v[88:89]
	v_pk_mul_f32 v[82:83], v[50:51], v[90:91] op_sel_hi:[1,0]
	v_pk_add_f32 v[52:53], v[170:171], v[52:53]
	v_pk_mul_f32 v[80:81], v[48:49], v[90:91] op_sel_hi:[1,0]
	v_pk_add_f32 v[52:53], v[104:105], v[52:53]
	v_pk_mul_f32 v[86:87], v[54:55], v[90:91] op_sel_hi:[1,0]
	v_pk_add_f32 v[52:53], v[172:173], v[52:53]
	v_pk_mul_f32 v[58:59], v[58:59], v[90:91] op_sel_hi:[1,0]
	v_pk_add_f32 v[52:53], v[106:107], v[52:53]
	v_pk_mul_f32 v[56:57], v[56:57], v[90:91] op_sel_hi:[1,0]
	v_pk_add_f32 v[52:53], v[174:175], v[52:53]
	v_pk_mul_f32 v[50:51], v[62:63], v[90:91] op_sel_hi:[1,0]
	v_pk_add_f32 v[52:53], v[108:109], v[52:53]
	v_pk_mul_f32 v[48:49], v[60:61], v[90:91] op_sel_hi:[1,0]
	v_pk_add_f32 v[52:53], v[176:177], v[52:53]
	v_mov_b32_e32 v91, v178
	v_pk_add_f32 v[52:53], v[110:111], v[52:53]
	v_cvt_pk_bf16_f32 v60, v170, v104
	v_add_u32_e32 v104, 0x6800, v206
	v_pk_fma_f32 v[120:121], v[120:121], v[90:91], v[52:53]
	ds_read2_b64 v[88:91], v104 offset1:4
	v_add_u32_e32 v105, 0x9000, v203
	v_cvt_pk_bf16_f32 v52, v154, v156
	v_cvt_pk_bf16_f32 v53, v158, v160
	v_cvt_pk_bf16_f32 v54, v162, v164
	v_cvt_pk_bf16_f32 v55, v166, v168
	s_waitcnt lgkmcnt(0)
; DEVI unsigned pk_bf16(float lo, float hi) { unsigned r; asm("v_cvt_pk_bf16_f32 %0, %1, %2" : "=v"(r) : "v"(lo), "v"(hi)); return r; }
; DEVI bf16x8 mk8(uint2 a, uint2 b) { union { uint4 u; bf16x8 v; } c; c.u = make_uint4(a.x, a.y, b.x, b.y); return c.v; }
; #define MFMA(a, b, c) __builtin_amdgcn_mfma_f32_16x16x32_bf16((a), (b), (c), 0, 0, 0)
; template <int DK, bool BIAS> ...
;     ...
;         {
;           const float alpha = __builtin_amdgcn_exp2f(mold - mnew);
;           lrun[qi] *= alpha;
; #pragma unroll
;           for (int et = 0; et < 4; ++et) O[et][qi] *= alpha;
;         }
;         lrun[qi] += ps;
; #pragma unroll
;         for (int k2 = 0; k2 < 2; ++k2) { uint2 lo, hi; lo.x = pk_bf16(S[2 * k2][qi][0], S[2 * k2][qi][1]); lo.y = pk_bf16(S[2 * k2][qi][2], S[2 * k2][qi][3]);
;           hi.x = pk_bf16(S[2 * k2 + 1][qi][0], S[2 * k2 + 1][qi][1]); hi.y = pk_bf16(S[2 * k2 + 1][qi][2], S[2 * k2 + 1][qi][3]); pf[qi][k2] = mk8(lo, hi); }
;       }
; #pragma unroll
;       for (int k2 = 0; k2 < 2; ++k2)
; #pragma unroll
;         for (int et = 0; et < 4; ++et) {
;           const uint2 v0 = *(const uint2*)(Vtm + (buf * 64 + 16 * et + fr) * 72 + 32 * k2 + 4 * fq), v1 = *(const uint2*)(Vtm + (buf * 64 + 16 * et + fr) * 72 + 32 * k2 + 16 + 4 * fq);
;           const bf16x8 va = mk8(v0, v1);
; #pragma unroll
;           for (int qi = 0; qi < 2; ++qi) O[et][qi] = MFMA(va, pf[qi][k2], O[et][qi]);
;         }
	v_mfma_f32_16x16x32_bf16 v[92:95], v[88:91], v[68:71], v[100:103]
	v_cvt_pk_bf16_f32 v61, v172, v106
	v_add_u32_e32 v106, 0x9800, v203
	v_pk_mul_f32 v[72:73], v[72:73], v[178:179] op_sel_hi:[1,0]
	v_mfma_f32_16x16x32_bf16 v[80:83], v[88:91], v[52:55], v[80:83]
	ds_read2_b64 v[88:91], v105 offset0:160 offset1:164
	v_cvt_pk_bf16_f32 v77, v173, v107
	v_add_u32_e32 v107, 0xa000, v203
	s_waitcnt lgkmcnt(0)
	v_mfma_f32_16x16x32_bf16 v[96:99], v[88:91], v[68:71], v[96:99]
	v_mul_f32_e64 v66, v78, v178
	v_mul_f32_e64 v67, v79, v178
	v_cvt_pk_bf16_f32 v78, v175, v109
	v_cvt_pk_bf16_f32 v79, v177, v111
	v_mfma_f32_16x16x32_bf16 v[84:87], v[88:91], v[52:55], v[84:87]
	ds_read2_b64 v[88:91], v106 offset0:192 offset1:196
	v_cvt_pk_bf16_f32 v62, v174, v108
	v_cvt_pk_bf16_f32 v63, v176, v110
	s_waitcnt lgkmcnt(0)
	v_mfma_f32_16x16x32_bf16 v[72:75], v[88:91], v[68:71], v[72:75]
	v_mov_b32_e32 v208, v209
	v_mov_b32_e32 v154, v131
	v_mfma_f32_16x16x32_bf16 v[56:59], v[88:91], v[52:55], v[56:59]
	ds_read2_b64 v[88:91], v107 offset0:224 offset1:228
	s_waitcnt lgkmcnt(0)
	v_mfma_f32_16x16x32_bf16 v[100:103], v[88:91], v[68:71], v[64:67]
	v_mfma_f32_16x16x32_bf16 v[88:91], v[88:91], v[52:55], v[48:51]
	ds_read2_b64 v[52:55], v105 offset0:168 offset1:172
	s_nop 1
	ds_read2_b64 v[48:51], v104 offset0:8 offset1:12
	s_waitcnt lgkmcnt(0)
	v_mfma_f32_16x16x32_bf16 v[64:67], v[48:51], v[76:79], v[92:95]
	v_mfma_f32_16x16x32_bf16 v[48:51], v[48:51], v[60:63], v[80:83]
	s_nop 2
	ds_read2_b64 v[80:83], v106 offset0:200 offset1:204
	s_waitcnt lgkmcnt(0)
	v_mfma_f32_16x16x32_bf16 v[72:75], v[80:83], v[76:79], v[72:75]
	v_mfma_f32_16x16x32_bf16 v[56:59], v[80:83], v[60:63], v[56:59]
	ds_read2_b64 v[80:83], v107 offset0:232 offset1:236
	v_mfma_f32_16x16x32_bf16 v[68:71], v[52:55], v[76:79], v[96:99]
	v_mfma_f32_16x16x32_bf16 v[52:55], v[52:55], v[60:63], v[84:87]
	s_waitcnt lgkmcnt(0)
	v_mfma_f32_16x16x32_bf16 v[76:79], v[80:83], v[76:79], v[100:103]
	v_mfma_f32_16x16x32_bf16 v[60:63], v[80:83], v[60:63], v[88:91]
